# scan: odd waves finish the readout before their first LDS reads of the next chunk, even waves after (de-phasing without idle delay)
# baseline (speedup 1.0000x reference)
; DI void scan_task(const Params& p, int l, int isP, int b, int h, int rg, char* smem, const bool dry) {
;     ...
;     f32x4 w4 = *(const f32x4*)fw, a4 = *(const f32x4*)fa, b4 = *(const f32x4*)fb;
;     uint2 ur = *(const uint2*)pr, uk = *(const uint2*)pk;
;     float v = vb[0];
; #pragma unroll
;     for (int s = 0; s < 32; s++) {
;       f32x4 w4n = w4, a4n = a4, b4n = b4;
;       uint2 urn = ur, ukn = uk;
;       float vn = v;
;       if (s < 31) {
;         w4n = *(const f32x4*)(fw + (s + 1) * 64);
;         a4n = *(const f32x4*)(fa + (s + 1) * 64);
;         b4n = *(const f32x4*)(fb + (s + 1) * 64);
;         urn = *(const uint2*)(pr + (s + 1) * 128);
;         ukn = *(const uint2*)(pk + (s + 1) * 128);
;         vn = vb[(s + 1) * 16];
;       }
;       __builtin_amdgcn_sched_barrier(0);
;       const f32x2 klo = {__uint_as_float(uk.x << 16), __uint_as_float(uk.x & 0xFFFF0000u)};
;       const f32x2 khi = {__uint_as_float(uk.y << 16), __uint_as_float(uk.y & 0xFFFF0000u)};
;       const f32x2 rlo = {__uint_as_float(ur.x << 16), __uint_as_float(ur.x & 0xFFFF0000u)};
;       const f32x2 rhi = {__uint_as_float(ur.y << 16), __uint_as_float(ur.y & 0xFFFF0000u)};
;       const f32x2 vv = {v, v};
;       const f32x2 t = Sa * a4.lo + Sb * a4.hi;
;       const f32x2 na = Sa * w4.lo + vv * klo;
;       const f32x2 nb = Sb * w4.hi + vv * khi;
;       float sa = t.x + t.y;
;       float yp = yprev;
;       rowsum16x2(sa, yp);
;       if (s >= 1 && s <= 16) ykeep0 = (jq == s - 1) ? yp : ykeep0;
;       if (s >= 17) ykeep1 = (jq == s - 17) ? yp : ykeep1;
;       const f32x2 sv = {sa, sa};
;       Sa = na + sv * b4.lo;
;       Sb = nb + sv * b4.hi;
;       const f32x2 yy = Sa * rlo + Sb * rhi;
;       yprev = yy.x + yy.y;
;       w4 = w4n; a4 = a4n; b4 = b4n; ur = urn; uk = ukn; v = vn;
;     }
;     {
;       const float yl = rowsum16(yprev);
;       ykeep1 = (jq == 15) ? yl : ykeep1;
;     }
;     if (!dry) { yo[0] = ykeep0; yo[(size_t)16 * 512] = ykeep1; }
.Lscan_noldA:
	s_waitcnt lgkmcnt(0)
	s_barrier
	s_bitcmp1_b32 s28, 0
	s_cbranch_scc1 .Lscan_oddA
	s_bitcmp1_b32 s28, 1
	s_cbranch_scc0 .Lscan_ndA
	s_nop 7
.Lscan_ndA:
	ds_read_b128 v[12:15], v76 offset:25600
	ds_read_b128 v[24:27], v76 offset:37888
	ds_read_b128 v[48:51], v77 offset:41984
	ds_read_b128 v[8:11], v76 offset:21504
	ds_read_b128 v[16:19], v76 offset:29696
	ds_read_b128 v[20:23], v76 offset:33792
	ds_read_b128 v[32:35], v76 offset:25856
	ds_read_b128 v[44:47], v76 offset:38144
	ds_read_b128 v[28:31], v76 offset:21760
	ds_read_b128 v[36:39], v76 offset:29952
	ds_read_b128 v[40:43], v76 offset:34048
	v_add_f32_dpp v75, v66, v66 row_mirror row_mask:0xf bank_mask:0x3
	v_add_f32_dpp v74, v74, v74 row_half_mirror row_mask:0xf bank_mask:0x5
	v_add_f32_dpp v68, v68, v68 quad_perm:[1,0,3,2] row_mask:0xf bank_mask:0xf
	v_add_f32_dpp v75, v67, v67 row_mirror row_mask:0xf bank_mask:0xc
	v_add_f32_dpp v70, v70, v70 quad_perm:[1,0,3,2] row_mask:0xf bank_mask:0xf
	v_add_f32_dpp v72, v72, v72 quad_perm:[1,0,3,2] row_mask:0xf bank_mask:0xf
	v_add_f32_dpp v74, v75, v75 row_half_mirror row_mask:0xf bank_mask:0xa
	v_add_f32_dpp v68, v68, v68 quad_perm:[2,3,0,1] row_mask:0xf bank_mask:0xf
	v_add_f32_dpp v70, v70, v70 quad_perm:[2,3,0,1] row_mask:0xf bank_mask:0xf
	v_add_f32_dpp v74, v74, v74 quad_perm:[1,0,3,2] row_mask:0xf bank_mask:0xf
	v_add_f32_dpp v72, v72, v72 quad_perm:[2,3,0,1] row_mask:0xf bank_mask:0xf
	v_cndmask_b32_e64 v68, v68, v70, s[18:19]
	v_add_f32_dpp v74, v74, v74 quad_perm:[2,3,0,1] row_mask:0xf bank_mask:0xf
	v_cndmask_b32_e64 v72, v72, v74, s[18:19]
	v_cndmask_b32_e64 v68, v68, v72, s[20:21]
	global_store_dword v83, v68, s[14:15]
	s_add_u32 s14, s14, 0x8000
	s_addc_u32 s15, s15, 0
	s_branch .Lscan_jA
.Lscan_oddA:
	s_bitcmp1_b32 s28, 1
	s_cbranch_scc0 .Lscan_nd2A
	s_nop 7
.Lscan_nd2A:
	v_add_f32_dpp v75, v66, v66 row_mirror row_mask:0xf bank_mask:0x3
	v_add_f32_dpp v74, v74, v74 row_half_mirror row_mask:0xf bank_mask:0x5
	v_add_f32_dpp v68, v68, v68 quad_perm:[1,0,3,2] row_mask:0xf bank_mask:0xf
	v_add_f32_dpp v75, v67, v67 row_mirror row_mask:0xf bank_mask:0xc
	v_add_f32_dpp v70, v70, v70 quad_perm:[1,0,3,2] row_mask:0xf bank_mask:0xf
	v_add_f32_dpp v72, v72, v72 quad_perm:[1,0,3,2] row_mask:0xf bank_mask:0xf
	v_add_f32_dpp v74, v75, v75 row_half_mirror row_mask:0xf bank_mask:0xa
	v_add_f32_dpp v68, v68, v68 quad_perm:[2,3,0,1] row_mask:0xf bank_mask:0xf
	v_add_f32_dpp v70, v70, v70 quad_perm:[2,3,0,1] row_mask:0xf bank_mask:0xf
	v_add_f32_dpp v74, v74, v74 quad_perm:[1,0,3,2] row_mask:0xf bank_mask:0xf
	v_add_f32_dpp v72, v72, v72 quad_perm:[2,3,0,1] row_mask:0xf bank_mask:0xf
	v_cndmask_b32_e64 v68, v68, v70, s[18:19]
	v_add_f32_dpp v74, v74, v74 quad_perm:[2,3,0,1] row_mask:0xf bank_mask:0xf
	v_cndmask_b32_e64 v72, v72, v74, s[18:19]
	v_cndmask_b32_e64 v68, v68, v72, s[20:21]
	global_store_dword v83, v68, s[14:15]
	s_add_u32 s14, s14, 0x8000
	s_addc_u32 s15, s15, 0
	ds_read_b128 v[12:15], v76 offset:25600
	ds_read_b128 v[24:27], v76 offset:37888
	ds_read_b128 v[48:51], v77 offset:41984
	ds_read_b128 v[8:11], v76 offset:21504
	ds_read_b128 v[16:19], v76 offset:29696
	ds_read_b128 v[20:23], v76 offset:33792
	ds_read_b128 v[32:35], v76 offset:25856
	ds_read_b128 v[44:47], v76 offset:38144
	ds_read_b128 v[28:31], v76 offset:21760
	ds_read_b128 v[36:39], v76 offset:29952
	ds_read_b128 v[40:43], v76 offset:34048
.Lscan_jA:
.Lscan_bodyB:
	s_waitcnt lgkmcnt(6)
	ds_read_b128 v[228:231], v76 offset:26112
	ds_read_b128 v[240:243], v76 offset:38400
	ds_read_b128 v[224:227], v76 offset:22016
	ds_read_b128 v[232:235], v76 offset:30208
	ds_read_b128 v[236:239], v76 offset:34304
	v_pk_mul_f32 v[56:57], v[4:5], v[12:13]
	v_pk_fma_f32 v[56:57], v[6:7], v[14:15], v[56:57]
	v_add_f32_e32 v58, v56, v57
	v_pk_mul_f32 v[60:61], v[48:49], v[24:25] op_sel_hi:[0,1]
	v_pk_mul_f32 v[62:63], v[48:49], v[26:27] op_sel_hi:[0,1]
	v_add_f32_dpp v58, v58, v58 quad_perm:[1,0,3,2] row_mask:0xf bank_mask:0xf bound_ctrl:1
	v_pk_fma_f32 v[60:61], v[4:5], v[8:9], v[60:61]
	v_pk_fma_f32 v[62:63], v[6:7], v[10:11], v[62:63]
	v_add_f32_dpp v58, v58, v58 quad_perm:[2,3,0,1] row_mask:0xf bank_mask:0xf bound_ctrl:1
	s_nop 1
	v_add_f32_dpp v58, v58, v58 row_half_mirror row_mask:0xf bank_mask:0xf bound_ctrl:1
	s_nop 1
	v_add_f32_dpp v58, v58, v58 row_mirror row_mask:0xf bank_mask:0xf bound_ctrl:1
	v_pk_fma_f32 v[4:5], v[58:59], v[16:17], v[60:61] op_sel_hi:[0,1,1]
	v_pk_fma_f32 v[6:7], v[58:59], v[18:19], v[62:63] op_sel_hi:[0,1,1]
	s_waitcnt lgkmcnt(6)
	ds_read_b128 v[12:15], v76 offset:26368
	ds_read_b128 v[24:27], v76 offset:38656
	ds_read_b128 v[8:11], v76 offset:22272
	ds_read_b128 v[16:19], v76 offset:30464
	ds_read_b128 v[52:55], v77 offset:42000
	v_pk_mul_f32 v[56:57], v[4:5], v[32:33]
	v_pk_mul_f32 v[64:65], v[4:5], v[20:21]
	v_pk_fma_f32 v[56:57], v[6:7], v[34:35], v[56:57]
	v_pk_fma_f32 v[64:65], v[6:7], v[22:23], v[64:65]
	v_add_f32_e32 v58, v56, v57
	v_pk_mul_f32 v[60:61], v[48:49], v[44:45] op_sel:[1,0] op_sel_hi:[1,1]
	v_pk_mul_f32 v[62:63], v[48:49], v[46:47] op_sel:[1,0] op_sel_hi:[1,1]
	v_add_f32_dpp v58, v58, v58 quad_perm:[1,0,3,2] row_mask:0xf bank_mask:0xf bound_ctrl:1
	v_pk_fma_f32 v[60:61], v[4:5], v[28:29], v[60:61]
	v_add_f32_e32 v66, v64, v65
	v_add_f32_dpp v58, v58, v58 quad_perm:[2,3,0,1] row_mask:0xf bank_mask:0xf bound_ctrl:1
	v_pk_fma_f32 v[62:63], v[6:7], v[30:31], v[62:63]
	s_nop 0
	v_add_f32_dpp v58, v58, v58 row_half_mirror row_mask:0xf bank_mask:0xf bound_ctrl:1
	ds_read_b128 v[20:23], v76 offset:34560
	s_nop 0
	v_add_f32_dpp v58, v58, v58 row_mirror row_mask:0xf bank_mask:0xf bound_ctrl:1
	v_pk_fma_f32 v[4:5], v[58:59], v[36:37], v[60:61] op_sel_hi:[0,1,1]
	v_pk_fma_f32 v[6:7], v[58:59], v[38:39], v[62:63] op_sel_hi:[0,1,1]
	s_waitcnt lgkmcnt(7)
; DI void scan_task(const Params& p, int l, int isP, int b, int h, int rg, char* smem, const bool dry) {
;     ...
;     for (int s = 0; s < 32; s++) {
;       f32x4 w4n = w4, a4n = a4, b4n = b4;
;       uint2 urn = ur, ukn = uk;
;       float vn = v;
;       if (s < 31) {
;         w4n = *(const f32x4*)(fw + (s + 1) * 64);
;         a4n = *(const f32x4*)(fa + (s + 1) * 64);
;         b4n = *(const f32x4*)(fb + (s + 1) * 64);
;         urn = *(const uint2*)(pr + (s + 1) * 128);
;         ukn = *(const uint2*)(pk + (s + 1) * 128);
;         vn = vb[(s + 1) * 16];
;       }
;       __builtin_amdgcn_sched_barrier(0);
;       const f32x2 klo = {__uint_as_float(uk.x << 16), __uint_as_float(uk.x & 0xFFFF0000u)};
;       const f32x2 khi = {__uint_as_float(uk.y << 16), __uint_as_float(uk.y & 0xFFFF0000u)};
;       const f32x2 rlo = {__uint_as_float(ur.x << 16), __uint_as_float(ur.x & 0xFFFF0000u)};
;       const f32x2 rhi = {__uint_as_float(ur.y << 16), __uint_as_float(ur.y & 0xFFFF0000u)};
;       const f32x2 vv = {v, v};
;       const f32x2 t = Sa * a4.lo + Sb * a4.hi;
;       const f32x2 na = Sa * w4.lo + vv * klo;
;       const f32x2 nb = Sb * w4.hi + vv * khi;
;       float sa = t.x + t.y;
;       float yp = yprev;
;       rowsum16x2(sa, yp);
;       if (s >= 1 && s <= 16) ykeep0 = (jq == s - 1) ? yp : ykeep0;
;       if (s >= 17) ykeep1 = (jq == s - 17) ? yp : ykeep1;
;       const f32x2 sv = {sa, sa};
;       Sa = na + sv * b4.lo;
;       Sb = nb + sv * b4.hi;
;       const f32x2 yy = Sa * rlo + Sb * rhi;
;       yprev = yy.x + yy.y;
;       w4 = w4n; a4 = a4n; b4 = b4n; ur = urn; uk = ukn; v = vn;
;     }
	ds_read_b128 v[32:35], v76 offset:26624
	ds_read_b128 v[44:47], v76 offset:38912
	ds_read_b128 v[28:31], v76 offset:22528
	ds_read_b128 v[36:39], v76 offset:30720
	v_pk_mul_f32 v[56:57], v[4:5], v[228:229]
	v_pk_mul_f32 v[64:65], v[4:5], v[40:41]
	v_pk_fma_f32 v[56:57], v[6:7], v[230:231], v[56:57]
	v_pk_fma_f32 v[64:65], v[6:7], v[42:43], v[64:65]
	v_add_f32_e32 v58, v56, v57
	v_pk_mul_f32 v[60:61], v[50:51], v[240:241] op_sel_hi:[0,1]
	v_pk_mul_f32 v[62:63], v[50:51], v[242:243] op_sel_hi:[0,1]
	v_add_f32_dpp v58, v58, v58 quad_perm:[1,0,3,2] row_mask:0xf bank_mask:0xf bound_ctrl:1
	v_pk_fma_f32 v[60:61], v[4:5], v[224:225], v[60:61]
	v_add_f32_e32 v67, v64, v65
	v_add_f32_dpp v58, v58, v58 quad_perm:[2,3,0,1] row_mask:0xf bank_mask:0xf bound_ctrl:1
	v_pk_fma_f32 v[62:63], v[6:7], v[226:227], v[62:63]
	v_add_f32_dpp v68, v66, v66 row_mirror row_mask:0xf bank_mask:0x3
	v_add_f32_dpp v58, v58, v58 row_half_mirror row_mask:0xf bank_mask:0xf bound_ctrl:1
	s_nop 0
	v_add_f32_dpp v68, v67, v67 row_mirror row_mask:0xf bank_mask:0xc
	ds_read_b128 v[40:43], v76 offset:34816
	v_add_f32_dpp v58, v58, v58 row_mirror row_mask:0xf bank_mask:0xf bound_ctrl:1
	v_pk_fma_f32 v[4:5], v[58:59], v[232:233], v[60:61] op_sel_hi:[0,1,1]
	v_pk_fma_f32 v[6:7], v[58:59], v[234:235], v[62:63] op_sel_hi:[0,1,1]
	s_waitcnt lgkmcnt(7)
	ds_read_b128 v[228:231], v76 offset:26880
	ds_read_b128 v[240:243], v76 offset:39168
	ds_read_b128 v[224:227], v76 offset:22784
	ds_read_b128 v[232:235], v76 offset:30976
	v_pk_mul_f32 v[56:57], v[4:5], v[12:13]
	v_pk_mul_f32 v[64:65], v[4:5], v[236:237]
	v_pk_fma_f32 v[56:57], v[6:7], v[14:15], v[56:57]
	v_pk_fma_f32 v[64:65], v[6:7], v[238:239], v[64:65]
	v_add_f32_e32 v58, v56, v57
	v_pk_mul_f32 v[60:61], v[50:51], v[24:25] op_sel:[1,0] op_sel_hi:[1,1]
	v_pk_mul_f32 v[62:63], v[50:51], v[26:27] op_sel:[1,0] op_sel_hi:[1,1]
	v_add_f32_dpp v58, v58, v58 quad_perm:[1,0,3,2] row_mask:0xf bank_mask:0xf bound_ctrl:1
	v_pk_fma_f32 v[60:61], v[4:5], v[8:9], v[60:61]
	v_add_f32_e32 v66, v64, v65
	v_add_f32_dpp v58, v58, v58 quad_perm:[2,3,0,1] row_mask:0xf bank_mask:0xf bound_ctrl:1
	v_pk_fma_f32 v[62:63], v[6:7], v[10:11], v[62:63]
	s_nop 0
	v_add_f32_dpp v58, v58, v58 row_half_mirror row_mask:0xf bank_mask:0xf bound_ctrl:1
	ds_read_b128 v[236:239], v76 offset:35072
	s_nop 0
	v_add_f32_dpp v58, v58, v58 row_mirror row_mask:0xf bank_mask:0xf bound_ctrl:1
	v_pk_fma_f32 v[4:5], v[58:59], v[16:17], v[60:61] op_sel_hi:[0,1,1]
	v_pk_fma_f32 v[6:7], v[58:59], v[18:19], v[62:63] op_sel_hi:[0,1,1]
	s_waitcnt lgkmcnt(6)
	ds_read_b128 v[12:15], v76 offset:27136
	ds_read_b128 v[24:27], v76 offset:39424
	ds_read_b128 v[8:11], v76 offset:23040
	ds_read_b128 v[16:19], v76 offset:31232
	v_pk_mul_f32 v[56:57], v[4:5], v[32:33]
	v_pk_mul_f32 v[64:65], v[4:5], v[20:21]
	v_pk_fma_f32 v[56:57], v[6:7], v[34:35], v[56:57]
	v_pk_fma_f32 v[64:65], v[6:7], v[22:23], v[64:65]
	v_add_f32_e32 v58, v56, v57
	v_pk_mul_f32 v[60:61], v[52:53], v[44:45] op_sel_hi:[0,1]
	v_pk_mul_f32 v[62:63], v[52:53], v[46:47] op_sel_hi:[0,1]
	v_add_f32_dpp v58, v58, v58 quad_perm:[1,0,3,2] row_mask:0xf bank_mask:0xf bound_ctrl:1
	v_pk_fma_f32 v[60:61], v[4:5], v[28:29], v[60:61]
	v_add_f32_e32 v67, v64, v65
	v_add_f32_dpp v58, v58, v58 quad_perm:[2,3,0,1] row_mask:0xf bank_mask:0xf bound_ctrl:1
	v_pk_fma_f32 v[62:63], v[6:7], v[30:31], v[62:63]
	v_add_f32_dpp v69, v66, v66 row_mirror row_mask:0xf bank_mask:0x3
	v_add_f32_dpp v58, v58, v58 row_half_mirror row_mask:0xf bank_mask:0xf bound_ctrl:1
	s_nop 0
	v_add_f32_dpp v69, v67, v67 row_mirror row_mask:0xf bank_mask:0xc
	ds_read_b128 v[20:23], v76 offset:35328
	v_add_f32_dpp v58, v58, v58 row_mirror row_mask:0xf bank_mask:0xf bound_ctrl:1
	v_pk_fma_f32 v[4:5], v[58:59], v[36:37], v[60:61] op_sel_hi:[0,1,1]
	v_pk_fma_f32 v[6:7], v[58:59], v[38:39], v[62:63] op_sel_hi:[0,1,1]
	s_waitcnt lgkmcnt(6)
	ds_read_b128 v[32:35], v76 offset:27392
	ds_read_b128 v[44:47], v76 offset:39680
	ds_read_b128 v[28:31], v76 offset:23296
	ds_read_b128 v[36:39], v76 offset:31488
	ds_read_b128 v[48:51], v77 offset:42016
	v_pk_mul_f32 v[56:57], v[4:5], v[228:229]
	v_pk_mul_f32 v[64:65], v[4:5], v[40:41]
	v_pk_fma_f32 v[56:57], v[6:7], v[230:231], v[56:57]
	v_pk_fma_f32 v[64:65], v[6:7], v[42:43], v[64:65]
	v_add_f32_e32 v58, v56, v57
	v_pk_mul_f32 v[60:61], v[52:53], v[240:241] op_sel:[1,0] op_sel_hi:[1,1]
	v_pk_mul_f32 v[62:63], v[52:53], v[242:243] op_sel:[1,0] op_sel_hi:[1,1]
	v_add_f32_dpp v58, v58, v58 quad_perm:[1,0,3,2] row_mask:0xf bank_mask:0xf bound_ctrl:1
	v_pk_fma_f32 v[60:61], v[4:5], v[224:225], v[60:61]
	v_add_f32_e32 v66, v64, v65
	v_add_f32_dpp v58, v58, v58 quad_perm:[2,3,0,1] row_mask:0xf bank_mask:0xf bound_ctrl:1
	v_pk_fma_f32 v[62:63], v[6:7], v[226:227], v[62:63]
	v_add_f32_dpp v68, v68, v68 row_half_mirror row_mask:0xf bank_mask:0x5
	v_add_f32_dpp v58, v58, v58 row_half_mirror row_mask:0xf bank_mask:0xf bound_ctrl:1
	s_nop 0
	v_add_f32_dpp v68, v69, v69 row_half_mirror row_mask:0xf bank_mask:0xa
	ds_read_b128 v[40:43], v76 offset:35584
	v_add_f32_dpp v58, v58, v58 row_mirror row_mask:0xf bank_mask:0xf bound_ctrl:1
	v_pk_fma_f32 v[4:5], v[58:59], v[232:233], v[60:61] op_sel_hi:[0,1,1]
	v_pk_fma_f32 v[6:7], v[58:59], v[234:235], v[62:63] op_sel_hi:[0,1,1]
	s_waitcnt lgkmcnt(7)
; DI void scan_task(const Params& p, int l, int isP, int b, int h, int rg, char* smem, const bool dry) {
;     ...
;     for (int s = 0; s < 32; s++) {
;       f32x4 w4n = w4, a4n = a4, b4n = b4;
;       uint2 urn = ur, ukn = uk;
;       float vn = v;
;       if (s < 31) {
;         w4n = *(const f32x4*)(fw + (s + 1) * 64);
;         a4n = *(const f32x4*)(fa + (s + 1) * 64);
;         b4n = *(const f32x4*)(fb + (s + 1) * 64);
;         urn = *(const uint2*)(pr + (s + 1) * 128);
;         ukn = *(const uint2*)(pk + (s + 1) * 128);
;         vn = vb[(s + 1) * 16];
;       }
;       __builtin_amdgcn_sched_barrier(0);
;       const f32x2 klo = {__uint_as_float(uk.x << 16), __uint_as_float(uk.x & 0xFFFF0000u)};
;       const f32x2 khi = {__uint_as_float(uk.y << 16), __uint_as_float(uk.y & 0xFFFF0000u)};
;       const f32x2 rlo = {__uint_as_float(ur.x << 16), __uint_as_float(ur.x & 0xFFFF0000u)};
;       const f32x2 rhi = {__uint_as_float(ur.y << 16), __uint_as_float(ur.y & 0xFFFF0000u)};
;       const f32x2 vv = {v, v};
;       const f32x2 t = Sa * a4.lo + Sb * a4.hi;
;       const f32x2 na = Sa * w4.lo + vv * klo;
;       const f32x2 nb = Sb * w4.hi + vv * khi;
;       float sa = t.x + t.y;
;       float yp = yprev;
;       rowsum16x2(sa, yp);
;       if (s >= 1 && s <= 16) ykeep0 = (jq == s - 1) ? yp : ykeep0;
;       if (s >= 17) ykeep1 = (jq == s - 17) ? yp : ykeep1;
;       const f32x2 sv = {sa, sa};
;       Sa = na + sv * b4.lo;
;       Sb = nb + sv * b4.hi;
;       const f32x2 yy = Sa * rlo + Sb * rhi;
;       yprev = yy.x + yy.y;
;       w4 = w4n; a4 = a4n; b4 = b4n; ur = urn; uk = ukn; v = vn;
;     }
	ds_read_b128 v[228:231], v76 offset:27648
	ds_read_b128 v[240:243], v76 offset:39936
	ds_read_b128 v[224:227], v76 offset:23552
	ds_read_b128 v[232:235], v76 offset:31744
	v_pk_mul_f32 v[56:57], v[4:5], v[12:13]
	v_pk_mul_f32 v[64:65], v[4:5], v[236:237]
	v_pk_fma_f32 v[56:57], v[6:7], v[14:15], v[56:57]
	v_pk_fma_f32 v[64:65], v[6:7], v[238:239], v[64:65]
	v_add_f32_e32 v58, v56, v57
	v_pk_mul_f32 v[60:61], v[54:55], v[24:25] op_sel_hi:[0,1]
	v_pk_mul_f32 v[62:63], v[54:55], v[26:27] op_sel_hi:[0,1]
	v_add_f32_dpp v58, v58, v58 quad_perm:[1,0,3,2] row_mask:0xf bank_mask:0xf bound_ctrl:1
	v_pk_fma_f32 v[60:61], v[4:5], v[8:9], v[60:61]
	v_add_f32_e32 v67, v64, v65
	v_add_f32_dpp v58, v58, v58 quad_perm:[2,3,0,1] row_mask:0xf bank_mask:0xf bound_ctrl:1
	v_pk_fma_f32 v[62:63], v[6:7], v[10:11], v[62:63]
	v_add_f32_dpp v70, v66, v66 row_mirror row_mask:0xf bank_mask:0x3
	v_add_f32_dpp v58, v58, v58 row_half_mirror row_mask:0xf bank_mask:0xf bound_ctrl:1
	s_nop 0
	v_add_f32_dpp v70, v67, v67 row_mirror row_mask:0xf bank_mask:0xc
	ds_read_b128 v[236:239], v76 offset:35840
	v_add_f32_dpp v58, v58, v58 row_mirror row_mask:0xf bank_mask:0xf bound_ctrl:1
	v_pk_fma_f32 v[4:5], v[58:59], v[16:17], v[60:61] op_sel_hi:[0,1,1]
	v_pk_fma_f32 v[6:7], v[58:59], v[18:19], v[62:63] op_sel_hi:[0,1,1]
	s_waitcnt lgkmcnt(7)
	ds_read_b128 v[12:15], v76 offset:27904
	ds_read_b128 v[24:27], v76 offset:40192
	ds_read_b128 v[8:11], v76 offset:23808
	ds_read_b128 v[16:19], v76 offset:32000
	v_pk_mul_f32 v[56:57], v[4:5], v[32:33]
	v_pk_mul_f32 v[64:65], v[4:5], v[20:21]
	v_pk_fma_f32 v[56:57], v[6:7], v[34:35], v[56:57]
	v_pk_fma_f32 v[64:65], v[6:7], v[22:23], v[64:65]
	v_add_f32_e32 v58, v56, v57
	v_pk_mul_f32 v[60:61], v[54:55], v[44:45] op_sel:[1,0] op_sel_hi:[1,1]
	v_pk_mul_f32 v[62:63], v[54:55], v[46:47] op_sel:[1,0] op_sel_hi:[1,1]
	v_add_f32_dpp v58, v58, v58 quad_perm:[1,0,3,2] row_mask:0xf bank_mask:0xf bound_ctrl:1
	v_pk_fma_f32 v[60:61], v[4:5], v[28:29], v[60:61]
	v_add_f32_e32 v66, v64, v65
	v_add_f32_dpp v58, v58, v58 quad_perm:[2,3,0,1] row_mask:0xf bank_mask:0xf bound_ctrl:1
	v_pk_fma_f32 v[62:63], v[6:7], v[30:31], v[62:63]
	s_nop 0
	v_add_f32_dpp v58, v58, v58 row_half_mirror row_mask:0xf bank_mask:0xf bound_ctrl:1
	ds_read_b128 v[20:23], v76 offset:36096
	s_nop 0
	v_add_f32_dpp v58, v58, v58 row_mirror row_mask:0xf bank_mask:0xf bound_ctrl:1
	v_pk_fma_f32 v[4:5], v[58:59], v[36:37], v[60:61] op_sel_hi:[0,1,1]
	v_pk_fma_f32 v[6:7], v[58:59], v[38:39], v[62:63] op_sel_hi:[0,1,1]
	s_waitcnt lgkmcnt(6)
	ds_read_b128 v[32:35], v76 offset:28160
	ds_read_b128 v[44:47], v76 offset:40448
	ds_read_b128 v[28:31], v76 offset:24064
	ds_read_b128 v[36:39], v76 offset:32256
	v_pk_mul_f32 v[56:57], v[4:5], v[228:229]
	v_pk_mul_f32 v[64:65], v[4:5], v[40:41]
	v_pk_fma_f32 v[56:57], v[6:7], v[230:231], v[56:57]
	v_pk_fma_f32 v[64:65], v[6:7], v[42:43], v[64:65]
	v_add_f32_e32 v58, v56, v57
	v_pk_mul_f32 v[60:61], v[48:49], v[240:241] op_sel_hi:[0,1]
	v_pk_mul_f32 v[62:63], v[48:49], v[242:243] op_sel_hi:[0,1]
	v_add_f32_dpp v58, v58, v58 quad_perm:[1,0,3,2] row_mask:0xf bank_mask:0xf bound_ctrl:1
	v_pk_fma_f32 v[60:61], v[4:5], v[224:225], v[60:61]
	v_add_f32_e32 v67, v64, v65
	v_add_f32_dpp v58, v58, v58 quad_perm:[2,3,0,1] row_mask:0xf bank_mask:0xf bound_ctrl:1
	v_pk_fma_f32 v[62:63], v[6:7], v[226:227], v[62:63]
	v_add_f32_dpp v71, v66, v66 row_mirror row_mask:0xf bank_mask:0x3
	v_add_f32_dpp v58, v58, v58 row_half_mirror row_mask:0xf bank_mask:0xf bound_ctrl:1
	s_nop 0
	v_add_f32_dpp v71, v67, v67 row_mirror row_mask:0xf bank_mask:0xc
	ds_read_b128 v[40:43], v76 offset:36352
	v_add_f32_dpp v58, v58, v58 row_mirror row_mask:0xf bank_mask:0xf bound_ctrl:1
	v_pk_fma_f32 v[4:5], v[58:59], v[232:233], v[60:61] op_sel_hi:[0,1,1]
	v_pk_fma_f32 v[6:7], v[58:59], v[234:235], v[62:63] op_sel_hi:[0,1,1]
	s_waitcnt lgkmcnt(6)
	ds_read_b128 v[228:231], v76 offset:28416
	ds_read_b128 v[240:243], v76 offset:40704
	ds_read_b128 v[224:227], v76 offset:24320
	ds_read_b128 v[232:235], v76 offset:32512
	ds_read_b128 v[52:55], v77 offset:42032
	v_pk_mul_f32 v[56:57], v[4:5], v[12:13]
	v_pk_mul_f32 v[64:65], v[4:5], v[236:237]
	v_pk_fma_f32 v[56:57], v[6:7], v[14:15], v[56:57]
	v_pk_fma_f32 v[64:65], v[6:7], v[238:239], v[64:65]
	v_add_f32_e32 v58, v56, v57
	v_pk_mul_f32 v[60:61], v[48:49], v[24:25] op_sel:[1,0] op_sel_hi:[1,1]
	v_pk_mul_f32 v[62:63], v[48:49], v[26:27] op_sel:[1,0] op_sel_hi:[1,1]
	v_add_f32_dpp v58, v58, v58 quad_perm:[1,0,3,2] row_mask:0xf bank_mask:0xf bound_ctrl:1
	v_pk_fma_f32 v[60:61], v[4:5], v[8:9], v[60:61]
	v_add_f32_e32 v66, v64, v65
	v_add_f32_dpp v58, v58, v58 quad_perm:[2,3,0,1] row_mask:0xf bank_mask:0xf bound_ctrl:1
	v_pk_fma_f32 v[62:63], v[6:7], v[10:11], v[62:63]
	v_add_f32_dpp v70, v70, v70 row_half_mirror row_mask:0xf bank_mask:0x5
	v_add_f32_dpp v58, v58, v58 row_half_mirror row_mask:0xf bank_mask:0xf bound_ctrl:1
	s_nop 0
	v_add_f32_dpp v70, v71, v71 row_half_mirror row_mask:0xf bank_mask:0xa
	ds_read_b128 v[236:239], v76 offset:36608
	v_add_f32_dpp v58, v58, v58 row_mirror row_mask:0xf bank_mask:0xf bound_ctrl:1
	v_pk_fma_f32 v[4:5], v[58:59], v[16:17], v[60:61] op_sel_hi:[0,1,1]
	v_pk_fma_f32 v[6:7], v[58:59], v[18:19], v[62:63] op_sel_hi:[0,1,1]
	s_waitcnt lgkmcnt(7)
; DI void scan_task(const Params& p, int l, int isP, int b, int h, int rg, char* smem, const bool dry) {
;     ...
;     for (int s = 0; s < 32; s++) {
;       f32x4 w4n = w4, a4n = a4, b4n = b4;
;       uint2 urn = ur, ukn = uk;
;       float vn = v;
;       if (s < 31) {
;         w4n = *(const f32x4*)(fw + (s + 1) * 64);
;         a4n = *(const f32x4*)(fa + (s + 1) * 64);
;         b4n = *(const f32x4*)(fb + (s + 1) * 64);
;         urn = *(const uint2*)(pr + (s + 1) * 128);
;         ukn = *(const uint2*)(pk + (s + 1) * 128);
;         vn = vb[(s + 1) * 16];
;       }
;       __builtin_amdgcn_sched_barrier(0);
;       const f32x2 klo = {__uint_as_float(uk.x << 16), __uint_as_float(uk.x & 0xFFFF0000u)};
;       const f32x2 khi = {__uint_as_float(uk.y << 16), __uint_as_float(uk.y & 0xFFFF0000u)};
;       const f32x2 rlo = {__uint_as_float(ur.x << 16), __uint_as_float(ur.x & 0xFFFF0000u)};
;       const f32x2 rhi = {__uint_as_float(ur.y << 16), __uint_as_float(ur.y & 0xFFFF0000u)};
;       const f32x2 vv = {v, v};
;       const f32x2 t = Sa * a4.lo + Sb * a4.hi;
;       const f32x2 na = Sa * w4.lo + vv * klo;
;       const f32x2 nb = Sb * w4.hi + vv * khi;
;       float sa = t.x + t.y;
;       float yp = yprev;
;       rowsum16x2(sa, yp);
;       if (s >= 1 && s <= 16) ykeep0 = (jq == s - 1) ? yp : ykeep0;
;       if (s >= 17) ykeep1 = (jq == s - 17) ? yp : ykeep1;
;       const f32x2 sv = {sa, sa};
;       Sa = na + sv * b4.lo;
;       Sb = nb + sv * b4.hi;
;       const f32x2 yy = Sa * rlo + Sb * rhi;
;       yprev = yy.x + yy.y;
;       w4 = w4n; a4 = a4n; b4 = b4n; ur = urn; uk = ukn; v = vn;
;     }
	ds_read_b128 v[12:15], v76 offset:28672
	ds_read_b128 v[24:27], v76 offset:40960
	ds_read_b128 v[8:11], v76 offset:24576
	ds_read_b128 v[16:19], v76 offset:32768
	v_pk_mul_f32 v[56:57], v[4:5], v[32:33]
	v_pk_mul_f32 v[64:65], v[4:5], v[20:21]
	v_pk_fma_f32 v[56:57], v[6:7], v[34:35], v[56:57]
	v_pk_fma_f32 v[64:65], v[6:7], v[22:23], v[64:65]
	v_add_f32_e32 v58, v56, v57
	v_pk_mul_f32 v[60:61], v[50:51], v[44:45] op_sel_hi:[0,1]
	v_pk_mul_f32 v[62:63], v[50:51], v[46:47] op_sel_hi:[0,1]
	v_add_f32_dpp v58, v58, v58 quad_perm:[1,0,3,2] row_mask:0xf bank_mask:0xf bound_ctrl:1
	v_pk_fma_f32 v[60:61], v[4:5], v[28:29], v[60:61]
	v_add_f32_e32 v67, v64, v65
	v_add_f32_dpp v58, v58, v58 quad_perm:[2,3,0,1] row_mask:0xf bank_mask:0xf bound_ctrl:1
	v_pk_fma_f32 v[62:63], v[6:7], v[30:31], v[62:63]
	v_add_f32_dpp v72, v66, v66 row_mirror row_mask:0xf bank_mask:0x3
	v_add_f32_dpp v58, v58, v58 row_half_mirror row_mask:0xf bank_mask:0xf bound_ctrl:1
	s_nop 0
	v_add_f32_dpp v72, v67, v67 row_mirror row_mask:0xf bank_mask:0xc
	ds_read_b128 v[20:23], v76 offset:36864
	v_add_f32_dpp v58, v58, v58 row_mirror row_mask:0xf bank_mask:0xf bound_ctrl:1
	v_pk_fma_f32 v[4:5], v[58:59], v[36:37], v[60:61] op_sel_hi:[0,1,1]
	v_pk_fma_f32 v[6:7], v[58:59], v[38:39], v[62:63] op_sel_hi:[0,1,1]
	s_waitcnt lgkmcnt(7)
	ds_read_b128 v[32:35], v76 offset:28928
	ds_read_b128 v[44:47], v76 offset:41216
	ds_read_b128 v[28:31], v76 offset:24832
	ds_read_b128 v[36:39], v76 offset:33024
	v_pk_mul_f32 v[56:57], v[4:5], v[228:229]
	v_pk_mul_f32 v[64:65], v[4:5], v[40:41]
	v_pk_fma_f32 v[56:57], v[6:7], v[230:231], v[56:57]
	v_pk_fma_f32 v[64:65], v[6:7], v[42:43], v[64:65]
	v_add_f32_e32 v58, v56, v57
	v_pk_mul_f32 v[60:61], v[50:51], v[240:241] op_sel:[1,0] op_sel_hi:[1,1]
	v_pk_mul_f32 v[62:63], v[50:51], v[242:243] op_sel:[1,0] op_sel_hi:[1,1]
	v_add_f32_dpp v58, v58, v58 quad_perm:[1,0,3,2] row_mask:0xf bank_mask:0xf bound_ctrl:1
	v_pk_fma_f32 v[60:61], v[4:5], v[224:225], v[60:61]
	v_add_f32_e32 v66, v64, v65
	v_add_f32_dpp v58, v58, v58 quad_perm:[2,3,0,1] row_mask:0xf bank_mask:0xf bound_ctrl:1
	v_pk_fma_f32 v[62:63], v[6:7], v[226:227], v[62:63]
	s_nop 0
	v_add_f32_dpp v58, v58, v58 row_half_mirror row_mask:0xf bank_mask:0xf bound_ctrl:1
	ds_read_b128 v[40:43], v76 offset:37120
	s_nop 0
	v_add_f32_dpp v58, v58, v58 row_mirror row_mask:0xf bank_mask:0xf bound_ctrl:1
	v_pk_fma_f32 v[4:5], v[58:59], v[232:233], v[60:61] op_sel_hi:[0,1,1]
	v_pk_fma_f32 v[6:7], v[58:59], v[234:235], v[62:63] op_sel_hi:[0,1,1]
	s_waitcnt lgkmcnt(6)
	ds_read_b128 v[228:231], v76 offset:29184
	ds_read_b128 v[240:243], v76 offset:41472
	ds_read_b128 v[224:227], v76 offset:25088
	ds_read_b128 v[232:235], v76 offset:33280
	v_pk_mul_f32 v[56:57], v[4:5], v[12:13]
	v_pk_mul_f32 v[64:65], v[4:5], v[236:237]
	v_pk_fma_f32 v[56:57], v[6:7], v[14:15], v[56:57]
	v_pk_fma_f32 v[64:65], v[6:7], v[238:239], v[64:65]
	v_add_f32_e32 v58, v56, v57
	v_pk_mul_f32 v[60:61], v[52:53], v[24:25] op_sel_hi:[0,1]
	v_pk_mul_f32 v[62:63], v[52:53], v[26:27] op_sel_hi:[0,1]
	v_add_f32_dpp v58, v58, v58 quad_perm:[1,0,3,2] row_mask:0xf bank_mask:0xf bound_ctrl:1
	v_pk_fma_f32 v[60:61], v[4:5], v[8:9], v[60:61]
	v_add_f32_e32 v67, v64, v65
	v_add_f32_dpp v58, v58, v58 quad_perm:[2,3,0,1] row_mask:0xf bank_mask:0xf bound_ctrl:1
	v_pk_fma_f32 v[62:63], v[6:7], v[10:11], v[62:63]
	v_add_f32_dpp v73, v66, v66 row_mirror row_mask:0xf bank_mask:0x3
	v_add_f32_dpp v58, v58, v58 row_half_mirror row_mask:0xf bank_mask:0xf bound_ctrl:1
	s_nop 0
	v_add_f32_dpp v73, v67, v67 row_mirror row_mask:0xf bank_mask:0xc
	ds_read_b128 v[236:239], v76 offset:37376
	v_add_f32_dpp v58, v58, v58 row_mirror row_mask:0xf bank_mask:0xf bound_ctrl:1
	v_pk_fma_f32 v[4:5], v[58:59], v[16:17], v[60:61] op_sel_hi:[0,1,1]
	v_pk_fma_f32 v[6:7], v[58:59], v[18:19], v[62:63] op_sel_hi:[0,1,1]
	s_waitcnt lgkmcnt(6)
; DI void scan_task(const Params& p, int l, int isP, int b, int h, int rg, char* smem, const bool dry) {
;     ...
;     for (int s = 0; s < 32; s++) {
;       f32x4 w4n = w4, a4n = a4, b4n = b4;
;       uint2 urn = ur, ukn = uk;
;       float vn = v;
;       if (s < 31) {
;         w4n = *(const f32x4*)(fw + (s + 1) * 64);
;         a4n = *(const f32x4*)(fa + (s + 1) * 64);
;         b4n = *(const f32x4*)(fb + (s + 1) * 64);
;         urn = *(const uint2*)(pr + (s + 1) * 128);
;         ukn = *(const uint2*)(pk + (s + 1) * 128);
;         vn = vb[(s + 1) * 16];
;       }
;       __builtin_amdgcn_sched_barrier(0);
;       const f32x2 klo = {__uint_as_float(uk.x << 16), __uint_as_float(uk.x & 0xFFFF0000u)};
;       const f32x2 khi = {__uint_as_float(uk.y << 16), __uint_as_float(uk.y & 0xFFFF0000u)};
;       const f32x2 rlo = {__uint_as_float(ur.x << 16), __uint_as_float(ur.x & 0xFFFF0000u)};
;       const f32x2 rhi = {__uint_as_float(ur.y << 16), __uint_as_float(ur.y & 0xFFFF0000u)};
;       const f32x2 vv = {v, v};
;       const f32x2 t = Sa * a4.lo + Sb * a4.hi;
;       const f32x2 na = Sa * w4.lo + vv * klo;
;       const f32x2 nb = Sb * w4.hi + vv * khi;
;       float sa = t.x + t.y;
;       float yp = yprev;
;       rowsum16x2(sa, yp);
;       if (s >= 1 && s <= 16) ykeep0 = (jq == s - 1) ? yp : ykeep0;
;       if (s >= 17) ykeep1 = (jq == s - 17) ? yp : ykeep1;
;       const f32x2 sv = {sa, sa};
;       Sa = na + sv * b4.lo;
;       Sb = nb + sv * b4.hi;
;       const f32x2 yy = Sa * rlo + Sb * rhi;
;       yprev = yy.x + yy.y;
;       w4 = w4n; a4 = a4n; b4 = b4n; ur = urn; uk = ukn; v = vn;
;     }
;     {
;       const float yl = rowsum16(yprev);
;       ykeep1 = (jq == 15) ? yl : ykeep1;
;     }
;     if (!dry) { yo[0] = ykeep0; yo[(size_t)16 * 512] = ykeep1; }
;     if (more) sstore((c + 1) & 1);
;     __syncthreads();
	ds_read_b128 v[12:15], v76 offset:29440
	ds_read_b128 v[24:27], v76 offset:41728
	ds_read_b128 v[8:11], v76 offset:25344
	ds_read_b128 v[16:19], v76 offset:33536
	v_pk_mul_f32 v[56:57], v[4:5], v[32:33]
	v_pk_mul_f32 v[64:65], v[4:5], v[20:21]
	v_pk_fma_f32 v[56:57], v[6:7], v[34:35], v[56:57]
	v_pk_fma_f32 v[64:65], v[6:7], v[22:23], v[64:65]
	v_add_f32_e32 v58, v56, v57
	v_pk_mul_f32 v[60:61], v[52:53], v[44:45] op_sel:[1,0] op_sel_hi:[1,1]
	v_pk_mul_f32 v[62:63], v[52:53], v[46:47] op_sel:[1,0] op_sel_hi:[1,1]
	v_add_f32_dpp v58, v58, v58 quad_perm:[1,0,3,2] row_mask:0xf bank_mask:0xf bound_ctrl:1
	v_pk_fma_f32 v[60:61], v[4:5], v[28:29], v[60:61]
	v_add_f32_e32 v66, v64, v65
	v_add_f32_dpp v58, v58, v58 quad_perm:[2,3,0,1] row_mask:0xf bank_mask:0xf bound_ctrl:1
	v_pk_fma_f32 v[62:63], v[6:7], v[30:31], v[62:63]
	v_add_f32_dpp v72, v72, v72 row_half_mirror row_mask:0xf bank_mask:0x5
	v_add_f32_dpp v58, v58, v58 row_half_mirror row_mask:0xf bank_mask:0xf bound_ctrl:1
	s_nop 0
	v_add_f32_dpp v72, v73, v73 row_half_mirror row_mask:0xf bank_mask:0xa
	ds_read_b128 v[20:23], v76 offset:37632
	v_add_f32_dpp v58, v58, v58 row_mirror row_mask:0xf bank_mask:0xf bound_ctrl:1
	v_pk_fma_f32 v[4:5], v[58:59], v[36:37], v[60:61] op_sel_hi:[0,1,1]
	v_pk_fma_f32 v[6:7], v[58:59], v[38:39], v[62:63] op_sel_hi:[0,1,1]
	s_waitcnt lgkmcnt(6)
	v_pk_mul_f32 v[56:57], v[4:5], v[228:229]
	v_pk_mul_f32 v[64:65], v[4:5], v[40:41]
	v_pk_fma_f32 v[56:57], v[6:7], v[230:231], v[56:57]
	v_pk_fma_f32 v[64:65], v[6:7], v[42:43], v[64:65]
	v_add_f32_e32 v58, v56, v57
	v_pk_mul_f32 v[60:61], v[54:55], v[240:241] op_sel_hi:[0,1]
	v_pk_mul_f32 v[62:63], v[54:55], v[242:243] op_sel_hi:[0,1]
	v_add_f32_dpp v58, v58, v58 quad_perm:[1,0,3,2] row_mask:0xf bank_mask:0xf bound_ctrl:1
	v_pk_fma_f32 v[60:61], v[4:5], v[224:225], v[60:61]
	v_add_f32_e32 v67, v64, v65
	v_add_f32_dpp v58, v58, v58 quad_perm:[2,3,0,1] row_mask:0xf bank_mask:0xf bound_ctrl:1
	v_pk_fma_f32 v[62:63], v[6:7], v[226:227], v[62:63]
	v_add_f32_dpp v74, v66, v66 row_mirror row_mask:0xf bank_mask:0x3
	v_add_f32_dpp v58, v58, v58 row_half_mirror row_mask:0xf bank_mask:0xf bound_ctrl:1
	s_nop 0
	v_add_f32_dpp v74, v67, v67 row_mirror row_mask:0xf bank_mask:0xc
	v_add_f32_dpp v58, v58, v58 row_mirror row_mask:0xf bank_mask:0xf bound_ctrl:1
	v_pk_fma_f32 v[4:5], v[58:59], v[232:233], v[60:61] op_sel_hi:[0,1,1]
	v_pk_fma_f32 v[6:7], v[58:59], v[234:235], v[62:63] op_sel_hi:[0,1,1]
	s_waitcnt lgkmcnt(1)
	v_pk_mul_f32 v[56:57], v[4:5], v[12:13]
	v_pk_mul_f32 v[64:65], v[4:5], v[236:237]
	v_pk_fma_f32 v[56:57], v[6:7], v[14:15], v[56:57]
	v_pk_fma_f32 v[64:65], v[6:7], v[238:239], v[64:65]
	v_add_f32_e32 v58, v56, v57
	v_pk_mul_f32 v[60:61], v[54:55], v[24:25] op_sel:[1,0] op_sel_hi:[1,1]
	v_pk_mul_f32 v[62:63], v[54:55], v[26:27] op_sel:[1,0] op_sel_hi:[1,1]
	v_add_f32_dpp v58, v58, v58 quad_perm:[1,0,3,2] row_mask:0xf bank_mask:0xf bound_ctrl:1
	v_pk_fma_f32 v[60:61], v[4:5], v[8:9], v[60:61]
	v_add_f32_e32 v66, v64, v65
	v_add_f32_dpp v58, v58, v58 quad_perm:[2,3,0,1] row_mask:0xf bank_mask:0xf bound_ctrl:1
	v_pk_fma_f32 v[62:63], v[6:7], v[10:11], v[62:63]
	s_nop 0
	v_add_f32_dpp v58, v58, v58 row_half_mirror row_mask:0xf bank_mask:0xf bound_ctrl:1
	s_nop 1
	v_add_f32_dpp v58, v58, v58 row_mirror row_mask:0xf bank_mask:0xf bound_ctrl:1
	v_pk_fma_f32 v[4:5], v[58:59], v[16:17], v[60:61] op_sel_hi:[0,1,1]
	v_pk_fma_f32 v[6:7], v[58:59], v[18:19], v[62:63] op_sel_hi:[0,1,1]
	s_waitcnt lgkmcnt(0)
	v_pk_mul_f32 v[64:65], v[4:5], v[20:21]
	v_pk_fma_f32 v[64:65], v[6:7], v[22:23], v[64:65]
	v_add_f32_e32 v67, v64, v65
	s_add_i32 s23, s16, 2
	s_cmp_lt_u32 s23, s17
	s_cbranch_scc0 .Lscan_lastB
	s_cmp_lg_u32 s22, 0
	s_cbranch_scc1 .Lscan_w6B
	s_waitcnt vmcnt(0)
	s_branch .Lscan_wdB

; DI void scan_task(const Params& p, int l, int isP, int b, int h, int rg, char* smem, const bool dry) {
;     ...
;     f32x4 w4 = *(const f32x4*)fw, a4 = *(const f32x4*)fa, b4 = *(const f32x4*)fb;
;     uint2 ur = *(const uint2*)pr, uk = *(const uint2*)pk;
;     float v = vb[0];
;     ...
;     {
;       const float yl = rowsum16(yprev);
;       ykeep1 = (jq == 15) ? yl : ykeep1;
;     }
;     if (!dry) { yo[0] = ykeep0; yo[(size_t)16 * 512] = ykeep1; }
.Lscan_ndB:
	ds_read_b128 v[12:15], v76 offset:4096
	ds_read_b128 v[24:27], v76 offset:16384
	ds_read_b128 v[48:51], v77 offset:20480
	ds_read_b128 v[8:11], v76 offset:0
	ds_read_b128 v[16:19], v76 offset:8192
	ds_read_b128 v[20:23], v76 offset:12288
	ds_read_b128 v[32:35], v76 offset:4352
	ds_read_b128 v[44:47], v76 offset:16640
	ds_read_b128 v[28:31], v76 offset:256
	ds_read_b128 v[36:39], v76 offset:8448
	ds_read_b128 v[40:43], v76 offset:12544
	v_add_f32_dpp v75, v66, v66 row_mirror row_mask:0xf bank_mask:0x3
	v_add_f32_dpp v74, v74, v74 row_half_mirror row_mask:0xf bank_mask:0x5
	v_add_f32_dpp v68, v68, v68 quad_perm:[1,0,3,2] row_mask:0xf bank_mask:0xf
	v_add_f32_dpp v75, v67, v67 row_mirror row_mask:0xf bank_mask:0xc
	v_add_f32_dpp v70, v70, v70 quad_perm:[1,0,3,2] row_mask:0xf bank_mask:0xf
	v_add_f32_dpp v72, v72, v72 quad_perm:[1,0,3,2] row_mask:0xf bank_mask:0xf
	v_add_f32_dpp v74, v75, v75 row_half_mirror row_mask:0xf bank_mask:0xa
	v_add_f32_dpp v68, v68, v68 quad_perm:[2,3,0,1] row_mask:0xf bank_mask:0xf
	v_add_f32_dpp v70, v70, v70 quad_perm:[2,3,0,1] row_mask:0xf bank_mask:0xf
	v_add_f32_dpp v74, v74, v74 quad_perm:[1,0,3,2] row_mask:0xf bank_mask:0xf
	v_add_f32_dpp v72, v72, v72 quad_perm:[2,3,0,1] row_mask:0xf bank_mask:0xf
	v_cndmask_b32_e64 v68, v68, v70, s[18:19]
	v_add_f32_dpp v74, v74, v74 quad_perm:[2,3,0,1] row_mask:0xf bank_mask:0xf
	v_cndmask_b32_e64 v72, v72, v74, s[18:19]
	v_cndmask_b32_e64 v68, v68, v72, s[20:21]
	global_store_dword v83, v68, s[14:15]
	s_add_u32 s14, s14, 0x8000
	s_addc_u32 s15, s15, 0
	s_branch .Lscan_jB

; DI void scan_task(const Params& p, int l, int isP, int b, int h, int rg, char* smem, const bool dry) {
;     ...
;     f32x4 w4 = *(const f32x4*)fw, a4 = *(const f32x4*)fa, b4 = *(const f32x4*)fb;
;     uint2 ur = *(const uint2*)pr, uk = *(const uint2*)pk;
;     float v = vb[0];
;     ...
;     {
;       const float yl = rowsum16(yprev);
;       ykeep1 = (jq == 15) ? yl : ykeep1;
;     }
;     if (!dry) { yo[0] = ykeep0; yo[(size_t)16 * 512] = ykeep1; }
.Lscan_nd2B:
	v_add_f32_dpp v75, v66, v66 row_mirror row_mask:0xf bank_mask:0x3
	v_add_f32_dpp v74, v74, v74 row_half_mirror row_mask:0xf bank_mask:0x5
	v_add_f32_dpp v68, v68, v68 quad_perm:[1,0,3,2] row_mask:0xf bank_mask:0xf
	v_add_f32_dpp v75, v67, v67 row_mirror row_mask:0xf bank_mask:0xc
	v_add_f32_dpp v70, v70, v70 quad_perm:[1,0,3,2] row_mask:0xf bank_mask:0xf
	v_add_f32_dpp v72, v72, v72 quad_perm:[1,0,3,2] row_mask:0xf bank_mask:0xf
	v_add_f32_dpp v74, v75, v75 row_half_mirror row_mask:0xf bank_mask:0xa
	v_add_f32_dpp v68, v68, v68 quad_perm:[2,3,0,1] row_mask:0xf bank_mask:0xf
	v_add_f32_dpp v70, v70, v70 quad_perm:[2,3,0,1] row_mask:0xf bank_mask:0xf
	v_add_f32_dpp v74, v74, v74 quad_perm:[1,0,3,2] row_mask:0xf bank_mask:0xf
	v_add_f32_dpp v72, v72, v72 quad_perm:[2,3,0,1] row_mask:0xf bank_mask:0xf
	v_cndmask_b32_e64 v68, v68, v70, s[18:19]
	v_add_f32_dpp v74, v74, v74 quad_perm:[2,3,0,1] row_mask:0xf bank_mask:0xf
	v_cndmask_b32_e64 v72, v72, v74, s[18:19]
	v_cndmask_b32_e64 v68, v68, v72, s[20:21]
	global_store_dword v83, v68, s[14:15]
	s_add_u32 s14, s14, 0x8000
	s_addc_u32 s15, s15, 0
	ds_read_b128 v[12:15], v76 offset:4096
	ds_read_b128 v[24:27], v76 offset:16384
	ds_read_b128 v[48:51], v77 offset:20480
	ds_read_b128 v[8:11], v76 offset:0
	ds_read_b128 v[16:19], v76 offset:8192
	ds_read_b128 v[20:23], v76 offset:12288
	ds_read_b128 v[32:35], v76 offset:4352
	ds_read_b128 v[44:47], v76 offset:16640
	ds_read_b128 v[28:31], v76 offset:256
	ds_read_b128 v[36:39], v76 offset:8448
	ds_read_b128 v[40:43], v76 offset:12544

; DI void scan_task(const Params& p, int l, int isP, int b, int h, int rg, char* smem, const bool dry) {
;     ...
;     {
;       const float yl = rowsum16(yprev);
;       ykeep1 = (jq == 15) ? yl : ykeep1;
;     }
;     if (!dry) { yo[0] = ykeep0; yo[(size_t)16 * 512] = ykeep1; }
;     ...
;     __syncthreads();
.Lscan_lastB:
	s_barrier
	v_add_f32_dpp v75, v66, v66 row_mirror row_mask:0xf bank_mask:0x3
	v_add_f32_dpp v74, v74, v74 row_half_mirror row_mask:0xf bank_mask:0x5
	v_add_f32_dpp v68, v68, v68 quad_perm:[1,0,3,2] row_mask:0xf bank_mask:0xf
	v_add_f32_dpp v75, v67, v67 row_mirror row_mask:0xf bank_mask:0xc
	v_add_f32_dpp v70, v70, v70 quad_perm:[1,0,3,2] row_mask:0xf bank_mask:0xf
	v_add_f32_dpp v72, v72, v72 quad_perm:[1,0,3,2] row_mask:0xf bank_mask:0xf
	v_add_f32_dpp v74, v75, v75 row_half_mirror row_mask:0xf bank_mask:0xa
	v_add_f32_dpp v68, v68, v68 quad_perm:[2,3,0,1] row_mask:0xf bank_mask:0xf
	v_add_f32_dpp v70, v70, v70 quad_perm:[2,3,0,1] row_mask:0xf bank_mask:0xf
	v_add_f32_dpp v74, v74, v74 quad_perm:[1,0,3,2] row_mask:0xf bank_mask:0xf
	v_add_f32_dpp v72, v72, v72 quad_perm:[2,3,0,1] row_mask:0xf bank_mask:0xf
	v_cndmask_b32_e64 v68, v68, v70, s[18:19]
	v_add_f32_dpp v74, v74, v74 quad_perm:[2,3,0,1] row_mask:0xf bank_mask:0xf
	v_cndmask_b32_e64 v72, v72, v74, s[18:19]
	v_cndmask_b32_e64 v68, v68, v72, s[20:21]
	global_store_dword v83, v68, s[14:15]
	s_add_u32 s14, s14, 0x8000
	s_addc_u32 s15, s15, 0
